# GEMM6 (ffn up): prefetch the 8 per-row sums of squares at the top of each tile into unused VGPRs; epilogue loads become moves
# baseline (speedup 1.0000x reference)
.LBB0_2095:
	s_lshl_b32 s0, s8, 8
	s_add_i32 s0, s0, s62
	v_or_b32_e32 v248, s0, v166
	v_lshlrev_b32_e32 v248, 2, v248
	global_load_dword v233, v248, s[16:17]
	global_load_dword v242, v248, s[16:17] offset:64
	global_load_dword v243, v248, s[16:17] offset:128
	global_load_dword v244, v248, s[16:17] offset:192
	global_load_dword v245, v248, s[16:17] offset:512
	global_load_dword v246, v248, s[16:17] offset:576
	global_load_dword v247, v248, s[16:17] offset:640
	global_load_dword v248, v248, s[16:17] offset:704
	s_add_i32 s58, s58, 1
	s_mul_i32 s0, s58, s60
	s_mul_hi_u32 s1, s58, s65
	s_add_i32 s1, s1, s0
	s_mul_i32 s0, s58, s65
	s_add_u32 s28, s0, s2
	s_addc_u32 s29, s1, s61
	v_cmp_gt_i64_e32 vcc, s[28:29], v[146:147]
	v_cmp_lt_i64_e64 s[4:5], s[28:29], v[144:145]
	s_cbranch_vccnz .LBB0_2097
	s_ashr_i32 s0, s28, 31
	s_lshr_b32 s0, s0, 29
	s_add_i32 s0, s28, s0
	s_ashr_i32 s1, s0, 3
	s_and_b32 s0, s0, -8
	s_sub_i32 s0, s28, s0
	s_cmp_lt_i32 s0, 0
	s_cselect_b32 s7, s66, 0xbb
	s_mul_i32 s0, s0, s7
	s_add_i32 s0, s0, s1
	s_mul_hi_i32 s1, s0, 0x2e8ba2e9
	s_lshr_b32 s7, s1, 31
	s_ashr_i32 s1, s1, 5
	s_add_i32 s1, s1, s7
	s_lshl_b32 s7, s1, 3
	s_sub_i32 s9, 0x44, s7
	s_min_i32 s9, s9, 8
	s_abs_i32 s24, s9
	v_cvt_f32_u32_e32 v2, s24
	s_sub_i32 s26, 0, s24
	s_mulk_i32 s1, 0xb0
	s_sub_i32 s0, s0, s1
	v_rcp_iflag_f32_e32 v2, v2
	s_abs_i32 s1, s0
	s_xor_b32 s25, s0, s9
	s_ashr_i32 s25, s25, 31
	v_mul_f32_e32 v2, 0x4f7ffffe, v2
	v_cvt_u32_f32_e32 v2, v2
	s_nop 0
	v_readfirstlane_b32 s27, v2
	s_mul_i32 s26, s26, s27
	s_mul_hi_u32 s26, s27, s26
	s_add_i32 s27, s27, s26
	s_mul_hi_u32 s26, s1, s27
	s_mul_i32 s27, s26, s24
	s_sub_i32 s1, s1, s27
	s_add_i32 s28, s26, 1
	s_sub_i32 s27, s1, s24
	s_cmp_ge_u32 s1, s24
	s_cselect_b32 s26, s28, s26
	s_cselect_b32 s1, s27, s1
	s_add_i32 s27, s26, 1
	s_cmp_ge_u32 s1, s24
	s_cselect_b32 s1, s27, s26
	s_xor_b32 s1, s1, s25
	s_sub_i32 s24, s1, s25
	s_mul_i32 s1, s24, s9
	s_sub_i32 s0, s0, s1
	s_add_i32 s26, s7, s0

.LBB0_2101:
	s_lshl_b32 s0, s8, 8
	s_add_i32 s0, s0, s62
	v_or_b32_e32 v150, s0, v166
	v_ashrrev_i32_e32 v151, 31, v150
	v_lshl_add_u64 v[152:153], v[150:151], 2, s[16:17]
	s_waitcnt vmcnt(8)
	v_mov_b32_e32 v138, v233
	v_or_b32_e32 v158, 16, v150
	v_or_b32_e32 v156, 32, v150
	v_or_b32_e32 v154, 48, v150
	v_ashrrev_i32_e32 v159, 31, v158
	v_ashrrev_i32_e32 v157, 31, v156
	v_ashrrev_i32_e32 v155, 31, v154
	v_lshl_add_u64 v[148:149], v[158:159], 2, s[16:17]
	v_lshl_add_u64 v[160:161], v[156:157], 2, s[16:17]
	v_lshl_add_u64 v[162:163], v[154:155], 2, s[16:17]
	v_mov_b32_e32 v157, v242
	v_mov_b32_e32 v155, v243
	v_mov_b32_e32 v151, v244
	v_lshl_or_b32 v148, s6, 8, v168
	v_mov_b64_e32 v[160:161], s[18:19]
	s_ashr_i32 s25, s0, 11
	v_add_u32_e32 v159, 0xffffc000, v150
	v_cmp_gt_i32_e64 s[6:7], s59, v150
	v_ashrrev_i32_e32 v149, 31, v148
	v_mov_b32_e32 v164, s25
	v_cndmask_b32_e64 v162, 7, v173, s[6:7]
	v_mad_i64_i32 v[160:161], s[0:1], v150, s70, v[160:161]
	v_lshrrev_b32_e32 v159, 3, v159
	v_and_b32_e32 v165, v162, v150
	v_cndmask_b32_e64 v183, -6, v174, s[6:7]
	v_cndmask_b32_e64 v184, 6, v175, s[6:7]
	v_cndmask_b32_e64 v188, v176, v177, s[6:7]
	v_lshl_add_u64 v[162:163], v[148:149], 1, v[160:161]
	v_cndmask_b32_e64 v159, v159, v164, s[6:7]
	v_lshlrev_b32_e32 v159, 1, v159
	v_add3_u32 v159, v165, v183, v159
	v_cmp_lt_i32_e32 vcc, s71, v148
	v_cmp_lt_u32_e64 s[8:9], v165, v184
	s_nor_b64 s[0:1], vcc, s[8:9]
	s_waitcnt vmcnt(0)
	v_fmamk_f32 v138, v138, 0x3a800000, v172
	v_mul_f32_e32 v160, 0x4b800000, v138
	v_cmp_gt_f32_e64 s[6:7], s69, v138
	s_nop 1
	v_cndmask_b32_e64 v138, v138, v160, s[6:7]
	v_rsq_f32_e32 v138, v138
	v_mad_i64_i32 v[160:161], s[10:11], v159, s70, 0
	v_mul_f32_e32 v159, 0x45800000, v138
	v_cndmask_b32_e64 v164, v138, v159, s[6:7]
	v_pk_mul_f32 v[128:129], v[128:129], v[164:165] op_sel_hi:[1,0]
	v_pk_mul_f32 v[126:127], v[126:127], v[164:165] op_sel_hi:[1,0]
	v_pk_mul_f32 v[124:125], v[124:125], v[164:165] op_sel_hi:[1,0]
	v_pk_mul_f32 v[122:123], v[122:123], v[164:165] op_sel_hi:[1,0]
	v_lshlrev_b32_e32 v138, 2, v188
	v_cvt_pk_bf16_f32 v184, v126, v127
	v_cvt_pk_bf16_f32 v185, v128, v129
	v_cvt_pk_bf16_f32 v186, v122, v123
	v_cvt_pk_bf16_f32 v187, v124, v125
	global_store_dwordx4 v[162:163], v[184:187], off
	s_and_saveexec_b64 s[6:7], s[0:1]
	s_cbranch_execz .LBB0_2103
	v_lshl_add_u64 v[184:185], s[44:45], 0, v[138:139]
	v_lshl_add_u64 v[184:185], v[184:185], 0, v[160:161]
	v_lshl_add_u64 v[184:185], v[148:149], 2, v[184:185]
	global_store_dwordx4 v[184:185], v[126:129], off
	global_store_dwordx4 v[184:185], v[122:125], off offset:16

.LBB0_2117:
	s_or_b64 exec, exec, s[8:9]
	v_mov_b32_e32 v70, v245
	v_mov_b32_e32 v75, v246
	v_mov_b32_e32 v74, v247
	v_mov_b32_e32 v72, v248
	v_add_u32_e32 v68, 0x80, v150
	v_add_u32_e32 v69, 0xffffc080, v150
	v_cmp_gt_i32_e64 s[8:9], s72, v150
	v_mov_b64_e32 v[66:67], s[18:19]
	v_ashrrev_i32_e32 v73, 11, v68
	v_cndmask_b32_e64 v71, 7, v173, s[8:9]
	v_lshrrev_b32_e32 v69, 3, v69
	v_mad_i64_i32 v[66:67], s[0:1], v68, s70, v[66:67]
	v_and_b32_e32 v71, v71, v68
	v_cndmask_b32_e64 v78, v69, v73, s[8:9]
	v_lshl_add_u64 v[68:69], v[148:149], 1, v[66:67]
	v_cndmask_b32_e64 v76, -6, v174, s[8:9]
	v_cndmask_b32_e64 v77, 6, v175, s[8:9]
	v_lshlrev_b32_e32 v66, 1, v78
	v_cndmask_b32_e64 v80, v176, v177, s[8:9]
	v_cmp_lt_u32_e64 s[8:9], v71, v77
	v_add3_u32 v66, v71, v76, v66
	s_nor_b64 s[0:1], vcc, s[8:9]
	v_lshlrev_b32_e32 v138, 2, v80
	s_waitcnt vmcnt(3)
	v_fmamk_f32 v67, v70, 0x3a800000, v172
	v_mul_f32_e32 v70, 0x4b800000, v67
	v_cmp_gt_f32_e64 s[10:11], s69, v67
	s_nop 1
	v_cndmask_b32_e64 v67, v67, v70, s[10:11]
	v_rsq_f32_e32 v70, v67
	v_mad_i64_i32 v[66:67], s[34:35], v66, s70, 0
	v_mul_f32_e32 v71, 0x45800000, v70
	v_cndmask_b32_e64 v70, v70, v71, s[10:11]
	v_pk_mul_f32 v[64:65], v[64:65], v[70:71] op_sel_hi:[1,0]
	v_pk_mul_f32 v[62:63], v[62:63], v[70:71] op_sel_hi:[1,0]
	v_pk_mul_f32 v[60:61], v[60:61], v[70:71] op_sel_hi:[1,0]
	v_pk_mul_f32 v[58:59], v[58:59], v[70:71] op_sel_hi:[1,0]
	v_cvt_pk_bf16_f32 v76, v62, v63
	v_cvt_pk_bf16_f32 v77, v64, v65
	v_cvt_pk_bf16_f32 v79, v60, v61
	s_nop 0
	v_cvt_pk_bf16_f32 v78, v58, v59
	global_store_dwordx4 v[68:69], v[76:79], off
	s_and_saveexec_b64 s[10:11], s[0:1]
	s_cbranch_execz .LBB0_2119
	v_lshl_add_u64 v[76:77], s[44:45], 0, v[138:139]
	v_lshl_add_u64 v[76:77], v[76:77], 0, v[66:67]
	v_lshl_add_u64 v[76:77], v[148:149], 2, v[76:77]
	global_store_dwordx4 v[76:77], v[62:65], off
	global_store_dwordx4 v[76:77], v[58:61], off offset:16
